# EpiResid epilogues (FFN-wo, w_out): residual loads issued 12-14 deep with counted vmcnt instead of one load-wait-store at a time
# baseline (speedup 1.0000x reference)
;     __device__ __forceinline__ void operator()(const f32x4 (&acc)[2][2][4][2], const Unit& u, int wr, int wc, int fr, int fq) const {
;         const int col0 = u.pn * BM + wc * 32 + 4 * fq;
; #pragma unroll
;         for (int ai = 0; ai < 2; ++ai) { if (ai * HALF >= rowmul) break;
; #pragma unroll
;             for (int m = 0; m < 4; ++m) { const size_t off = (size_t)(u.pm * rowmul + ai * HALF + wr * 64 + m * 16 + fr) * ldc + col0;
; #pragma unroll
;                 for (int bj = 0; bj < 2; ++bj)
; #pragma unroll
;                     for (int n = 0; n < 2; ++n) { const f32x4 bs = *(const f32x4*)(base + off + bj * HALF + n * 16);
;                         *(f32x4*)(out + off + bj * HALF + n * 16) = bs + acc[ai][bj][m][n] * alpha; } } }
;     }
.LBB0_329:
	s_lshl_b32 s0, s44, 8
	v_add_u32_e32 v140, s0, v151
	v_lshl_or_b32 v138, s45, 8, v156
	v_ashrrev_i32_e32 v141, 31, v140
	v_ashrrev_i32_e32 v139, 31, v138
	v_lshlrev_b64 v[218:219], 10, v[140:141]
	v_lshl_add_u64 v[218:219], v[218:219], 0, v[138:139]
	v_lshlrev_b64 v[218:219], 2, v[218:219]
	v_lshl_add_u64 v[220:221], s[14:15], 0, v[218:219]
	v_lshl_add_u64 v[218:219], s[8:9], 0, v[218:219]
	global_load_dwordx4 v[158:161], v[220:221], off
	global_load_dwordx4 v[162:165], v[220:221], off offset:64
	global_load_dwordx4 v[166:169], v[220:221], off offset:512
	global_load_dwordx4 v[170:173], v[220:221], off offset:576
	v_add_co_u32_e32 v138, vcc, 0x10000, v220
	s_nop 1
	v_addc_co_u32_e32 v139, vcc, 0, v221, vcc
	global_load_dwordx4 v[174:177], v[138:139], off
	global_load_dwordx4 v[178:181], v[138:139], off offset:64
	global_load_dwordx4 v[182:185], v[138:139], off offset:512
	global_load_dwordx4 v[186:189], v[138:139], off offset:576
	v_add_co_u32_e32 v138, vcc, 0x20000, v220
	s_nop 1
	v_addc_co_u32_e32 v139, vcc, 0, v221, vcc
	global_load_dwordx4 v[190:193], v[138:139], off
	global_load_dwordx4 v[198:201], v[138:139], off offset:64
	global_load_dwordx4 v[202:205], v[138:139], off offset:512
	global_load_dwordx4 v[206:209], v[138:139], off offset:576
	v_add_co_u32_e32 v138, vcc, 0x30000, v220
	s_nop 1
	v_addc_co_u32_e32 v139, vcc, 0, v221, vcc
	global_load_dwordx4 v[210:213], v[138:139], off
	global_load_dwordx4 v[214:217], v[138:139], off offset:64
	s_waitcnt vmcnt(13)
	v_pk_fma_f32 v[128:129], v[128:129], 0.5, v[160:161] op_sel_hi:[1,0,1]
	v_pk_fma_f32 v[126:127], v[126:127], 0.5, v[158:159] op_sel_hi:[1,0,1]
	global_store_dwordx4 v[218:219], v[126:129], off
	global_load_dwordx4 v[126:129], v[138:139], off offset:512
	s_waitcnt vmcnt(14)
	v_pk_fma_f32 v[124:125], v[124:125], 0.5, v[164:165] op_sel_hi:[1,0,1]
	v_pk_fma_f32 v[122:123], v[122:123], 0.5, v[162:163] op_sel_hi:[1,0,1]
	global_store_dwordx4 v[218:219], v[122:125], off offset:64
	global_load_dwordx4 v[122:125], v[138:139], off offset:576
	s_waitcnt vmcnt(15)
	v_pk_fma_f32 v[120:121], v[120:121], 0.5, v[168:169] op_sel_hi:[1,0,1]
	v_pk_fma_f32 v[118:119], v[118:119], 0.5, v[166:167] op_sel_hi:[1,0,1]
	global_store_dwordx4 v[218:219], v[118:121], off offset:512
	v_add_co_u32_e32 v138, vcc, 0x80000, v220
	s_nop 1
	v_addc_co_u32_e32 v139, vcc, 0, v221, vcc
	global_load_dwordx4 v[118:121], v[138:139], off
	s_waitcnt vmcnt(16)
	v_pk_fma_f32 v[108:109], v[108:109], 0.5, v[172:173] op_sel_hi:[1,0,1]
	v_pk_fma_f32 v[106:107], v[106:107], 0.5, v[170:171] op_sel_hi:[1,0,1]
	global_store_dwordx4 v[218:219], v[106:109], off offset:576
	global_load_dwordx4 v[106:109], v[138:139], off offset:64
	s_waitcnt vmcnt(17)
	v_pk_fma_f32 v[116:117], v[116:117], 0.5, v[176:177] op_sel_hi:[1,0,1]
	v_pk_fma_f32 v[114:115], v[114:115], 0.5, v[174:175] op_sel_hi:[1,0,1]
	v_add_co_u32_e32 v140, vcc, 0x10000, v218
	s_nop 1
	v_addc_co_u32_e32 v141, vcc, 0, v219, vcc
	global_store_dwordx4 v[140:141], v[114:117], off
	global_load_dwordx4 v[114:117], v[138:139], off offset:512
	s_waitcnt vmcnt(18)
	v_pk_fma_f32 v[112:113], v[112:113], 0.5, v[180:181] op_sel_hi:[1,0,1]
	v_pk_fma_f32 v[110:111], v[110:111], 0.5, v[178:179] op_sel_hi:[1,0,1]
	global_store_dwordx4 v[140:141], v[110:113], off offset:64
	global_load_dwordx4 v[110:113], v[138:139], off offset:576
	s_waitcnt vmcnt(19)
	v_pk_fma_f32 v[104:105], v[104:105], 0.5, v[184:185] op_sel_hi:[1,0,1]
	v_pk_fma_f32 v[102:103], v[102:103], 0.5, v[182:183] op_sel_hi:[1,0,1]
	global_store_dwordx4 v[140:141], v[102:105], off offset:512
	v_add_co_u32_e32 v138, vcc, 0x90000, v220
	s_nop 1
	v_addc_co_u32_e32 v139, vcc, 0, v221, vcc
	global_load_dwordx4 v[102:105], v[138:139], off
	s_waitcnt vmcnt(20)
	v_pk_fma_f32 v[92:93], v[92:93], 0.5, v[188:189] op_sel_hi:[1,0,1]
	v_pk_fma_f32 v[90:91], v[90:91], 0.5, v[186:187] op_sel_hi:[1,0,1]
	global_store_dwordx4 v[140:141], v[90:93], off offset:576
	global_load_dwordx4 v[90:93], v[138:139], off offset:64
	s_waitcnt vmcnt(21)
	v_pk_fma_f32 v[100:101], v[100:101], 0.5, v[192:193] op_sel_hi:[1,0,1]
	v_pk_fma_f32 v[98:99], v[98:99], 0.5, v[190:191] op_sel_hi:[1,0,1]
	v_add_co_u32_e32 v140, vcc, 0x20000, v218
	s_nop 1
	v_addc_co_u32_e32 v141, vcc, 0, v219, vcc
	global_store_dwordx4 v[140:141], v[98:101], off
	global_load_dwordx4 v[98:101], v[138:139], off offset:512
	s_waitcnt vmcnt(22)
	v_pk_fma_f32 v[96:97], v[96:97], 0.5, v[200:201] op_sel_hi:[1,0,1]
	v_pk_fma_f32 v[94:95], v[94:95], 0.5, v[198:199] op_sel_hi:[1,0,1]
	global_store_dwordx4 v[140:141], v[94:97], off offset:64
	global_load_dwordx4 v[94:97], v[138:139], off offset:576
	s_waitcnt vmcnt(23)
	v_pk_fma_f32 v[88:89], v[88:89], 0.5, v[204:205] op_sel_hi:[1,0,1]
	v_pk_fma_f32 v[86:87], v[86:87], 0.5, v[202:203] op_sel_hi:[1,0,1]
	global_store_dwordx4 v[140:141], v[86:89], off offset:512
	v_add_co_u32_e32 v138, vcc, 0xa0000, v220
	s_nop 1
	v_addc_co_u32_e32 v139, vcc, 0, v221, vcc
	global_load_dwordx4 v[86:89], v[138:139], off
	s_waitcnt vmcnt(24)
	v_pk_fma_f32 v[76:77], v[76:77], 0.5, v[208:209] op_sel_hi:[1,0,1]
	v_pk_fma_f32 v[74:75], v[74:75], 0.5, v[206:207] op_sel_hi:[1,0,1]
	global_store_dwordx4 v[140:141], v[74:77], off offset:576
	global_load_dwordx4 v[74:77], v[138:139], off offset:64
	s_waitcnt vmcnt(25)
; #define PG8_BAR __builtin_amdgcn_s_barrier()
;     __device__ __forceinline__ void operator()(const f32x4 (&acc)[2][2][4][2], const Unit& u, int wr, int wc, int fr, int fq) const {
;         const int col0 = u.pn * BM + wc * 32 + 4 * fq;
; #pragma unroll
;         for (int ai = 0; ai < 2; ++ai) { if (ai * HALF >= rowmul) break;
; #pragma unroll
;             for (int m = 0; m < 4; ++m) { const size_t off = (size_t)(u.pm * rowmul + ai * HALF + wr * 64 + m * 16 + fr) * ldc + col0;
; #pragma unroll
;                 for (int bj = 0; bj < 2; ++bj)
; #pragma unroll
;                     for (int n = 0; n < 2; ++n) { const f32x4 bs = *(const f32x4*)(base + off + bj * HALF + n * 16);
;                         *(f32x4*)(out + off + bj * HALF + n * 16) = bs + acc[ai][bj][m][n] * alpha; } } }
;     }
; template <class Epi, class Sched, bool ALIGN_EPI = false, bool SP2 = false, bool HALFM = false>
; __device__ __forceinline__ void gemm_phase(PG8_LAS unsigned char* lds, const Gemm g, const Sched& S, const Epi& E, const int tid_in) {
;     ...
;         if constexpr (ALIGN_EPI) { if (wr == 0) PG8_BAR; }
;         if constexpr (!Epi::AFTER_DRAIN) { E(acc, cur, wr, wc, fr, fq); S.done(cur); }
;         if (!has_next) break;
; #pragma unroll
;         for (int a = 0; a < 2; ++a)
; #pragma unroll
;             for (int b = 0; b < 2; ++b)
; #pragma unroll
;                 for (int m = 0; m < 4; ++m)
; #pragma unroll
;                     for (int n = 0; n < 2; ++n) acc[a][b][m][n] = (f32x4){0.f, 0.f, 0.f, 0.f};
;         cur = nxt; cA = nA; cB = nB; ++ui;
;         if constexpr (ALIGN_EPI) { if (wr == 1) PG8_BAR; }
	v_pk_fma_f32 v[84:85], v[84:85], 0.5, v[212:213] op_sel_hi:[1,0,1]
	v_pk_fma_f32 v[82:83], v[82:83], 0.5, v[210:211] op_sel_hi:[1,0,1]
	v_add_co_u32_e32 v140, vcc, 0x30000, v218
	s_nop 1
	v_addc_co_u32_e32 v141, vcc, 0, v219, vcc
	global_store_dwordx4 v[140:141], v[82:85], off
	global_load_dwordx4 v[82:85], v[138:139], off offset:512
	s_waitcnt vmcnt(26)
	v_pk_fma_f32 v[80:81], v[80:81], 0.5, v[216:217] op_sel_hi:[1,0,1]
	v_pk_fma_f32 v[78:79], v[78:79], 0.5, v[214:215] op_sel_hi:[1,0,1]
	global_store_dwordx4 v[140:141], v[78:81], off offset:64
	global_load_dwordx4 v[78:81], v[138:139], off offset:576
	s_waitcnt vmcnt(26)
	v_pk_fma_f32 v[72:73], v[72:73], 0.5, v[128:129] op_sel_hi:[1,0,1]
	v_pk_fma_f32 v[70:71], v[70:71], 0.5, v[126:127] op_sel_hi:[1,0,1]
	global_store_dwordx4 v[140:141], v[70:73], off offset:512
	v_add_co_u32_e32 v138, vcc, 0xb0000, v220
	s_nop 1
	v_addc_co_u32_e32 v139, vcc, 0, v221, vcc
	global_load_dwordx4 v[70:73], v[138:139], off
	s_waitcnt vmcnt(26)
	v_pk_fma_f32 v[68:69], v[68:69], 0.5, v[124:125] op_sel_hi:[1,0,1]
	v_pk_fma_f32 v[66:67], v[66:67], 0.5, v[122:123] op_sel_hi:[1,0,1]
	global_store_dwordx4 v[140:141], v[66:69], off offset:576
	global_load_dwordx4 v[66:69], v[138:139], off offset:64
	s_waitcnt vmcnt(26)
	v_pk_fma_f32 v[64:65], v[64:65], 0.5, v[120:121] op_sel_hi:[1,0,1]
	v_pk_fma_f32 v[62:63], v[62:63], 0.5, v[118:119] op_sel_hi:[1,0,1]
	v_add_co_u32_e32 v140, vcc, 0x80000, v218
	s_nop 1
	v_addc_co_u32_e32 v141, vcc, 0, v219, vcc
	global_store_dwordx4 v[140:141], v[62:65], off
	global_load_dwordx4 v[62:65], v[138:139], off offset:512
	s_waitcnt vmcnt(26)
	v_pk_fma_f32 v[60:61], v[60:61], 0.5, v[108:109] op_sel_hi:[1,0,1]
	v_pk_fma_f32 v[58:59], v[58:59], 0.5, v[106:107] op_sel_hi:[1,0,1]
	global_store_dwordx4 v[140:141], v[58:61], off offset:64
	global_load_dwordx4 v[58:61], v[138:139], off offset:576
	s_waitcnt vmcnt(26)
	v_pk_fma_f32 v[56:57], v[56:57], 0.5, v[116:117] op_sel_hi:[1,0,1]
	v_pk_fma_f32 v[54:55], v[54:55], 0.5, v[114:115] op_sel_hi:[1,0,1]
	global_store_dwordx4 v[140:141], v[54:57], off offset:512
	s_waitcnt vmcnt(25)
	v_pk_fma_f32 v[44:45], v[44:45], 0.5, v[112:113] op_sel_hi:[1,0,1]
	v_pk_fma_f32 v[42:43], v[42:43], 0.5, v[110:111] op_sel_hi:[1,0,1]
	global_store_dwordx4 v[140:141], v[42:45], off offset:576
	s_waitcnt vmcnt(24)
	v_pk_fma_f32 v[52:53], v[52:53], 0.5, v[104:105] op_sel_hi:[1,0,1]
	v_pk_fma_f32 v[50:51], v[50:51], 0.5, v[102:103] op_sel_hi:[1,0,1]
	v_add_co_u32_e32 v140, vcc, 0x90000, v218
	s_nop 1
	v_addc_co_u32_e32 v141, vcc, 0, v219, vcc
	global_store_dwordx4 v[140:141], v[50:53], off
	s_waitcnt vmcnt(23)
	v_pk_fma_f32 v[48:49], v[48:49], 0.5, v[92:93] op_sel_hi:[1,0,1]
	v_pk_fma_f32 v[46:47], v[46:47], 0.5, v[90:91] op_sel_hi:[1,0,1]
	global_store_dwordx4 v[140:141], v[46:49], off offset:64
	s_waitcnt vmcnt(22)
	v_pk_fma_f32 v[40:41], v[40:41], 0.5, v[100:101] op_sel_hi:[1,0,1]
	v_pk_fma_f32 v[38:39], v[38:39], 0.5, v[98:99] op_sel_hi:[1,0,1]
	global_store_dwordx4 v[140:141], v[38:41], off offset:512
	s_waitcnt vmcnt(21)
	v_pk_fma_f32 v[28:29], v[28:29], 0.5, v[96:97] op_sel_hi:[1,0,1]
	v_pk_fma_f32 v[26:27], v[26:27], 0.5, v[94:95] op_sel_hi:[1,0,1]
	global_store_dwordx4 v[140:141], v[26:29], off offset:576
	s_waitcnt vmcnt(20)
	v_pk_fma_f32 v[36:37], v[36:37], 0.5, v[88:89] op_sel_hi:[1,0,1]
	v_pk_fma_f32 v[34:35], v[34:35], 0.5, v[86:87] op_sel_hi:[1,0,1]
	v_add_co_u32_e32 v140, vcc, 0xa0000, v218
	s_nop 1
	v_addc_co_u32_e32 v141, vcc, 0, v219, vcc
	global_store_dwordx4 v[140:141], v[34:37], off
	s_waitcnt vmcnt(19)
	v_pk_fma_f32 v[32:33], v[32:33], 0.5, v[76:77] op_sel_hi:[1,0,1]
	v_pk_fma_f32 v[30:31], v[30:31], 0.5, v[74:75] op_sel_hi:[1,0,1]
	global_store_dwordx4 v[140:141], v[30:33], off offset:64
	s_waitcnt vmcnt(18)
	v_pk_fma_f32 v[24:25], v[24:25], 0.5, v[84:85] op_sel_hi:[1,0,1]
	v_pk_fma_f32 v[22:23], v[22:23], 0.5, v[82:83] op_sel_hi:[1,0,1]
	global_store_dwordx4 v[140:141], v[22:25], off offset:512
	s_waitcnt vmcnt(17)
	v_pk_fma_f32 v[12:13], v[12:13], 0.5, v[80:81] op_sel_hi:[1,0,1]
	v_pk_fma_f32 v[10:11], v[10:11], 0.5, v[78:79] op_sel_hi:[1,0,1]
	global_store_dwordx4 v[140:141], v[10:13], off offset:576
	s_waitcnt vmcnt(16)
	v_pk_fma_f32 v[20:21], v[20:21], 0.5, v[72:73] op_sel_hi:[1,0,1]
	v_pk_fma_f32 v[18:19], v[18:19], 0.5, v[70:71] op_sel_hi:[1,0,1]
	v_add_co_u32_e32 v140, vcc, 0xb0000, v218
	s_nop 1
	v_addc_co_u32_e32 v141, vcc, 0, v219, vcc
	global_store_dwordx4 v[140:141], v[18:21], off
	s_waitcnt vmcnt(15)
	v_pk_fma_f32 v[16:17], v[16:17], 0.5, v[68:69] op_sel_hi:[1,0,1]
	v_pk_fma_f32 v[14:15], v[14:15], 0.5, v[66:67] op_sel_hi:[1,0,1]
	global_store_dwordx4 v[140:141], v[14:17], off offset:64
	s_waitcnt vmcnt(14)
	v_pk_fma_f32 v[8:9], v[8:9], 0.5, v[64:65] op_sel_hi:[1,0,1]
	v_pk_fma_f32 v[6:7], v[6:7], 0.5, v[62:63] op_sel_hi:[1,0,1]
	global_store_dwordx4 v[140:141], v[6:9], off offset:512
	s_waitcnt vmcnt(13)
	v_pk_fma_f32 v[4:5], v[4:5], 0.5, v[60:61] op_sel_hi:[1,0,1]
	v_pk_fma_f32 v[2:3], v[2:3], 0.5, v[58:59] op_sel_hi:[1,0,1]
	global_store_dwordx4 v[140:141], v[2:5], off offset:576
	s_and_b64 vcc, exec, s[4:5]
	s_mov_b64 s[4:5], -1
	s_cbranch_vccnz .LBB0_314
	s_andn2_b64 vcc, exec, s[10:11]
	s_cbranch_vccnz .LBB0_313
	s_barrier
	s_branch .LBB0_313

;     __device__ __forceinline__ void operator()(const f32x4 (&acc)[2][2][4][2], const Unit& u, int wr, int wc, int fr, int fq) const {
;         const int col0 = u.pn * BM + wc * 32 + 4 * fq;
; #pragma unroll
;         for (int ai = 0; ai < 2; ++ai) { if (ai * HALF >= rowmul) break;
; #pragma unroll
;             for (int m = 0; m < 4; ++m) { const size_t off = (size_t)(u.pm * rowmul + ai * HALF + wr * 64 + m * 16 + fr) * ldc + col0;
; #pragma unroll
;                 for (int bj = 0; bj < 2; ++bj)
; #pragma unroll
;                     for (int n = 0; n < 2; ++n) { const f32x4 bs = *(const f32x4*)(base + off + bj * HALF + n * 16);
;                         *(f32x4*)(out + off + bj * HALF + n * 16) = bs + acc[ai][bj][m][n] * alpha; } } }
;     }
.LBB0_355:
	s_lshl_b32 s15, s22, 7
	v_add_u32_e32 v134, s15, v72
	v_lshl_or_b32 v70, s23, 8, v77
	v_ashrrev_i32_e32 v135, 31, v134
	v_ashrrev_i32_e32 v71, 31, v70
	v_lshlrev_b64 v[134:135], 12, v[134:135]
	v_lshl_add_u64 v[134:135], s[8:9], 0, v[134:135]
	v_lshlrev_b64 v[70:71], 2, v[70:71]
	v_lshl_add_u64 v[132:133], v[134:135], 0, v[70:71]
	global_load_dwordx4 v[80:83], v[132:133], off
	global_load_dwordx4 v[84:87], v[132:133], off offset:64
	global_load_dwordx4 v[88:91], v[132:133], off offset:512
	global_load_dwordx4 v[92:95], v[132:133], off offset:576
	v_add_co_u32_e32 v134, vcc, 0x10000, v132
	s_nop 1
	v_addc_co_u32_e32 v135, vcc, 0, v133, vcc
	global_load_dwordx4 v[96:99], v[134:135], off
	global_load_dwordx4 v[100:103], v[134:135], off offset:64
	global_load_dwordx4 v[104:107], v[134:135], off offset:512
	global_load_dwordx4 v[108:111], v[134:135], off offset:576
	v_add_co_u32_e32 v134, vcc, 0x20000, v132
	s_nop 1
	v_addc_co_u32_e32 v135, vcc, 0, v133, vcc
	global_load_dwordx4 v[112:115], v[134:135], off
	global_load_dwordx4 v[116:119], v[134:135], off offset:64
	global_load_dwordx4 v[120:123], v[134:135], off offset:512
	global_load_dwordx4 v[124:127], v[134:135], off offset:576
	s_waitcnt vmcnt(11)
	v_pk_add_f32 v[64:65], v[64:65], v[82:83]
	v_pk_add_f32 v[62:63], v[62:63], v[80:81]
	global_store_dwordx4 v[132:133], v[62:65], off
	v_add_co_u32_e32 v134, vcc, 0x30000, v132
	s_nop 1
	v_addc_co_u32_e32 v135, vcc, 0, v133, vcc
	global_load_dwordx4 v[62:65], v[134:135], off
	s_waitcnt vmcnt(12)
	v_pk_add_f32 v[60:61], v[60:61], v[86:87]
	v_pk_add_f32 v[58:59], v[58:59], v[84:85]
	global_store_dwordx4 v[132:133], v[58:61], off offset:64
	global_load_dwordx4 v[58:61], v[134:135], off offset:64
	s_waitcnt vmcnt(13)
	v_pk_add_f32 v[56:57], v[56:57], v[90:91]
	v_pk_add_f32 v[54:55], v[54:55], v[88:89]
	global_store_dwordx4 v[132:133], v[54:57], off offset:512
	global_load_dwordx4 v[54:57], v[134:135], off offset:512
	s_waitcnt vmcnt(14)
	v_pk_add_f32 v[52:53], v[52:53], v[94:95]
	v_pk_add_f32 v[50:51], v[50:51], v[92:93]
	global_store_dwordx4 v[132:133], v[50:53], off offset:576
	global_load_dwordx4 v[50:53], v[134:135], off offset:576
	s_waitcnt vmcnt(15)
	v_pk_add_f32 v[48:49], v[48:49], v[98:99]
	v_pk_add_f32 v[46:47], v[46:47], v[96:97]
	v_add_co_u32_e32 v136, vcc, 0x10000, v132
	s_nop 1
	v_addc_co_u32_e32 v137, vcc, 0, v133, vcc
	global_store_dwordx4 v[136:137], v[46:49], off
	s_waitcnt vmcnt(15)
	v_pk_add_f32 v[44:45], v[44:45], v[102:103]
	v_pk_add_f32 v[42:43], v[42:43], v[100:101]
	global_store_dwordx4 v[136:137], v[42:45], off offset:64
	s_waitcnt vmcnt(15)
	v_pk_add_f32 v[40:41], v[40:41], v[106:107]
	v_pk_add_f32 v[38:39], v[38:39], v[104:105]
	global_store_dwordx4 v[136:137], v[38:41], off offset:512
	s_waitcnt vmcnt(15)
	v_pk_add_f32 v[36:37], v[36:37], v[110:111]
	v_pk_add_f32 v[34:35], v[34:35], v[108:109]
	global_store_dwordx4 v[136:137], v[34:37], off offset:576
	s_waitcnt vmcnt(15)
	v_pk_add_f32 v[32:33], v[32:33], v[114:115]
	v_pk_add_f32 v[30:31], v[30:31], v[112:113]
	v_add_co_u32_e32 v136, vcc, 0x20000, v132
	s_nop 1
	v_addc_co_u32_e32 v137, vcc, 0, v133, vcc
	global_store_dwordx4 v[136:137], v[30:33], off
	s_waitcnt vmcnt(15)
	v_pk_add_f32 v[28:29], v[28:29], v[118:119]
	v_pk_add_f32 v[26:27], v[26:27], v[116:117]
	global_store_dwordx4 v[136:137], v[26:29], off offset:64
	s_waitcnt vmcnt(15)
	v_pk_add_f32 v[24:25], v[24:25], v[122:123]
	v_pk_add_f32 v[22:23], v[22:23], v[120:121]
	global_store_dwordx4 v[136:137], v[22:25], off offset:512
	s_waitcnt vmcnt(15)
	v_pk_add_f32 v[20:21], v[20:21], v[126:127]
	v_pk_add_f32 v[18:19], v[18:19], v[124:125]
	global_store_dwordx4 v[136:137], v[18:21], off offset:576
	s_waitcnt vmcnt(14)
	v_pk_add_f32 v[16:17], v[16:17], v[64:65]
	v_pk_add_f32 v[14:15], v[14:15], v[62:63]
	v_add_co_u32_e32 v136, vcc, 0x30000, v132
	s_nop 1
	v_addc_co_u32_e32 v137, vcc, 0, v133, vcc
	global_store_dwordx4 v[136:137], v[14:17], off
	s_waitcnt vmcnt(13)
	v_pk_add_f32 v[12:13], v[12:13], v[60:61]
	v_pk_add_f32 v[10:11], v[10:11], v[58:59]
	global_store_dwordx4 v[136:137], v[10:13], off offset:64
	s_waitcnt vmcnt(12)
	v_pk_add_f32 v[8:9], v[8:9], v[56:57]
	v_pk_add_f32 v[6:7], v[6:7], v[54:55]
	global_store_dwordx4 v[136:137], v[6:9], off offset:512
	s_waitcnt vmcnt(11)
	v_pk_add_f32 v[4:5], v[4:5], v[52:53]
	v_pk_add_f32 v[2:3], v[2:3], v[50:51]
	global_store_dwordx4 v[136:137], v[2:5], off offset:576
	s_mov_b64 s[22:23], -1
	s_andn2_b64 vcc, exec, s[4:5]
	s_cbranch_vccnz .LBB0_344
	s_andn2_b64 vcc, exec, s[6:7]
	s_cbranch_vccnz .LBB0_343
	s_barrier
	s_branch .LBB0_343
